# attention unit boundary: gain loads and combine reads batched, bias LUT rebuilt only when head changes, next unit index popped at tile-loop exit
# speedup vs baseline: 1.0064x; 1.0064x over previous
; __global__ void __launch_bounds__(512, 2) mk_fwd(Args a) {
;     ...
;             if (IN(4)) {
;                 int ll = lane; asm volatile("" : "+v"(ll));
;                 const float s1 = wave_sum(a.in[10][ll] * a.in[11][ll]), s2 = wave_sum(a.in[12][ll] * a.in[13][ll]);
;                 const float lam = __expf(s1) - __expf(s2) + 0.2f;
;                 att::attn_phase(lds, U3, VT, MIX, a.in[3], a.in[14], lam, (unsigned*)(ws + WS_CTL));
.LBB0_494:
	v_readlane_b32 s4, v254, 33
	v_readlane_b32 s5, v254, 34
	s_andn2_b64 vcc, exec, s[4:5]
	s_cbranch_vccnz .LBB0_611
	s_mov_b32 s32, -1
	s_mov_b32 s101, 0
	s_load_dwordx8 s[12:19], s[0:1], 0x50
	v_mov_b32_e32 v144, v203
	v_xor_b32_e32 v6, 2, v211
	v_ashrrev_i32_e32 v145, 31, v144
	s_waitcnt lgkmcnt(0)
	v_lshlrev_b64 v[0:1], 2, v[144:145]
	v_lshl_add_u64 v[2:3], s[12:13], 0, v[0:1]
	global_load_dword v4, v[2:3], off
	v_lshl_add_u64 v[2:3], s[14:15], 0, v[0:1]
	global_load_dword v5, v[2:3], off
	v_lshl_add_u64 v[2:3], s[16:17], 0, v[0:1]
	v_lshl_add_u64 v[0:1], s[18:19], 0, v[0:1]
	global_load_dword v2, v[2:3], off
	v_xor_b32_e32 v3, 1, v211
	global_load_dword v0, v[0:1], off
	v_and_b32_e32 v1, 64, v211
	v_add_u32_e32 v1, 64, v1
	v_cmp_lt_i32_e32 vcc, v3, v1
	v_xor_b32_e32 v7, 4, v211
	v_xor_b32_e32 v8, 8, v211
	v_cndmask_b32_e32 v3, v211, v3, vcc
	v_lshlrev_b32_e32 v3, 2, v3
	v_cmp_lt_i32_e32 vcc, v6, v1
	v_xor_b32_e32 v9, 16, v211
	v_xor_b32_e32 v10, 32, v211
	v_cndmask_b32_e32 v6, v211, v6, vcc
	v_lshlrev_b32_e32 v6, 2, v6
	v_cmp_lt_i32_e32 vcc, v7, v1
	s_mov_b32 s4, 0
	s_waitcnt vmcnt(2)
	v_mul_f32_e32 v11, v4, v5
	ds_bpermute_b32 v11, v3, v11
	s_waitcnt vmcnt(0)
	v_mul_f32_e32 v12, v2, v0
	ds_bpermute_b32 v3, v3, v12
	s_waitcnt lgkmcnt(1)
	v_fmac_f32_e32 v11, v4, v5
	v_cndmask_b32_e32 v4, v211, v7, vcc
	v_lshlrev_b32_e32 v4, 2, v4
	v_cmp_lt_i32_e32 vcc, v8, v1
	s_waitcnt lgkmcnt(0)
	v_fmac_f32_e32 v3, v2, v0
	ds_bpermute_b32 v0, v6, v11
	ds_bpermute_b32 v2, v6, v3
	v_cndmask_b32_e32 v5, v211, v8, vcc
	v_lshlrev_b32_e32 v5, 2, v5
	v_cmp_lt_i32_e32 vcc, v9, v1
	s_waitcnt lgkmcnt(1)
	v_add_f32_e32 v0, v11, v0
	s_waitcnt lgkmcnt(0)
	v_add_f32_e32 v2, v3, v2
	ds_bpermute_b32 v3, v4, v0
	ds_bpermute_b32 v4, v4, v2
	s_waitcnt lgkmcnt(1)
	v_add_f32_e32 v0, v0, v3
	s_waitcnt lgkmcnt(0)
	v_add_f32_e32 v2, v2, v4
	ds_bpermute_b32 v3, v5, v0
	ds_bpermute_b32 v4, v5, v2
	v_cndmask_b32_e32 v5, v211, v9, vcc
	v_lshlrev_b32_e32 v5, 2, v5
	v_cmp_lt_i32_e32 vcc, v10, v1
	s_waitcnt lgkmcnt(1)
	v_add_f32_e32 v0, v0, v3
	s_waitcnt lgkmcnt(0)
	v_add_f32_e32 v2, v2, v4
	ds_bpermute_b32 v3, v5, v0
	ds_bpermute_b32 v4, v5, v2
	v_cndmask_b32_e32 v1, v211, v10, vcc
	v_lshlrev_b32_e32 v145, 2, v1
	s_waitcnt lgkmcnt(1)
	v_add_f32_e32 v0, v0, v3
	s_waitcnt lgkmcnt(0)
	v_add_f32_e32 v1, v2, v4
	ds_bpermute_b32 v2, v145, v0
	ds_bpermute_b32 v3, v145, v1
	s_waitcnt lgkmcnt(1)
	v_add_f32_e32 v0, v0, v2
	s_waitcnt lgkmcnt(0)
	v_add_f32_e32 v1, v1, v3
	v_mul_f32_e32 v0, 0x3fb8aa3b, v0
	v_mul_f32_e32 v1, 0x3fb8aa3b, v1
	v_exp_f32_e32 v0, v0
	v_exp_f32_e32 v1, v1
	s_nop 0
	v_sub_f32_e32 v0, v0, v1
	v_add_f32_e32 v154, 0x3e4ccccd, v0
	s_branch .LBB0_497

; __device__ __forceinline__ void attn_phase(LAS unsigned char* lds, const bf16_t* U3, const bf16_t* VT, bf16_t* MIX, const float* tbl, const float* gain, float lam, unsigned* ctl) {
;     ...
;         for (;;) {
;             if (threadIdx.x == 0) misc[0] = (int)atomicAdd(ctl + x * 64, 1u);
;             __syncthreads();
;             const int idx = misc[0];
;             __syncthreads();
;             if (idx >= UNITS_PER_Q) break;
.LBB0_500:
	s_and_saveexec_b64 s[10:11], s[6:7]
	s_cbranch_execz .LBB0_504
	s_cmp_eq_u32 s101, 1
	s_cbranch_scc0 .Latt_popnow
	s_waitcnt vmcnt(0)
	v_readfirstlane_b32 s12, v183
	v_mov_b32_e32 v1, s42
	s_nop 0
	v_mov_b32_e32 v0, s12
	ds_write_b32 v1, v0
	s_branch .LBB0_504
.Latt_popnow:
	s_mov_b64 s[14:15], exec
	v_mbcnt_lo_u32_b32 v0, s14, 0
	v_mbcnt_hi_u32_b32 v0, s15, v0
	v_cmp_eq_u32_e32 vcc, 0, v0
	s_and_saveexec_b64 s[12:13], vcc
	s_cbranch_execz .LBB0_503
	s_bcnt1_i32_b64 s14, s[14:15]
	v_mov_b32_e32 v1, s14
	global_atomic_add v1, v161, v1, s[18:19] sc0

; __device__ __forceinline__ void attn_phase(LAS unsigned char* lds, const bf16_t* U3, const bf16_t* VT, bf16_t* MIX, const float* tbl, const float* gain, float lam, unsigned* ctl) {
;     ...
;             if (threadIdx.x == 0) misc[0] = (int)atomicAdd(ctl + x * 64, 1u);
;             __syncthreads();
;             const int idx = misc[0];
;             __syncthreads();
;             if (idx >= UNITS_PER_Q) break;
;             int grp, b, h, qb;
;             if (idx < 256) { const int i = idx >> 6; qb = idx & 63; const int p = x + 8 * i; grp = 1; b = p >> 2; h = p & 3; }
;             else { const int j = idx - 256, i = j >> 4; qb = j & 15; const int p = x + 8 * i; grp = 0; b = p >> 2; h = p & 3; }
.LBB0_504:
	s_or_b64 exec, exec, s[10:11]
	s_mov_b32 s101, 0
	v_mov_b32_e32 v0, s42
	s_waitcnt lgkmcnt(0)
	s_barrier
	ds_read_b32 v0, v0
	s_movk_i32 s10, 0x17f
	s_waitcnt lgkmcnt(0)
	s_barrier
	v_cmp_lt_i32_e32 vcc, s10, v0
	v_readfirstlane_b32 s14, v0
	s_mov_b64 s[10:11], -1
	s_cbranch_vccnz .LBB0_499
	s_cmpk_gt_i32 s14, 0xff
	s_cselect_b64 s[10:11], -1, 0
	s_mov_b64 s[12:13], -1
	s_and_b64 vcc, exec, s[10:11]
	s_cbranch_vccnz .LBB0_507
	s_ashr_i32 s12, s14, 3
	s_and_b32 s12, s12, -8
	s_or_b32 s12, s12, s5
	s_and_b32 s16, s14, 63
	s_ashr_i32 s17, s12, 2
	s_mov_b64 s[12:13], 0

; __device__ __forceinline__ void attn_unit(LAS unsigned char* lds, const bf16_t* __restrict__ U3, const bf16_t* __restrict__ VT, bf16_t* __restrict__ MIX, ...
;     ...
;     if (tid < 257) { const int rel = tid - 128, n = rel < 0 ? -rel : rel;
;         int bk = n < 8 ? n : 8 + (n >= 12) + (n >= 16) + (n >= 23) + (n >= 32) + (n >= 46) + (n >= 64) + (n >= 91);
;         if (rel > 0) bk += 16;
;         lut[tid] = tbl[bk * 4 + h] * LOG2E; }
.LBB0_509:
	v_mov_b32_e32 v155, v202
	s_movk_i32 s12, 0x200
	s_nop 0
	v_readfirstlane_b32 s73, v155
	s_cmp_eq_u32 s36, s32
	s_cbranch_scc1 .Latt_lutskip
	s_mov_b32 s32, s36
	v_cmp_gt_i32_e32 vcc, s12, v155
	s_and_saveexec_b64 s[12:13], vcc
	s_cbranch_execz .LBB0_513
	v_add_u32_e32 v0, 0xfffffee0, v155
	v_sub_u32_e32 v1, 0x120, v155
	v_cmp_gt_i32_e32 vcc, 0x120, v155
	s_nop 1
	v_cndmask_b32_e32 v0, v0, v1, vcc
	v_cmp_lt_i32_e32 vcc, 7, v0
	s_and_saveexec_b64 s[14:15], vcc
	s_cbranch_execz .LBB0_512
	v_cmp_lt_u32_e32 vcc, 11, v0
	s_movk_i32 s24, 0x5a
	s_nop 0
	v_cndmask_b32_e64 v1, 8, 9, vcc
	v_cmp_lt_u32_e32 vcc, 15, v0
	s_nop 1
	v_cndmask_b32_e64 v2, 0, 1, vcc
	v_cmp_lt_u32_e32 vcc, 22, v0
	s_nop 1
	v_addc_co_u32_e32 v1, vcc, v1, v2, vcc
	v_cmp_lt_u32_e32 vcc, 31, v0
	s_nop 1
	v_cndmask_b32_e64 v2, 0, 1, vcc
	v_cmp_lt_u32_e32 vcc, 45, v0
	s_nop 1
	v_addc_co_u32_e32 v1, vcc, v1, v2, vcc
	v_cmp_lt_u32_e32 vcc, 63, v0
	s_nop 1
	v_cndmask_b32_e64 v2, 0, 1, vcc
	v_cmp_lt_u32_e32 vcc, s24, v0
	s_nop 1
	v_addc_co_u32_e32 v0, vcc, v1, v2, vcc

; __device__ __forceinline__ void attn_unit(LAS unsigned char* lds, const bf16_t* __restrict__ U3, const bf16_t* __restrict__ VT, bf16_t* __restrict__ MIX, ...
;     ...
;     bf16x8 qr[4];
;     { const bf16_t* qp = U3 + (size_t)(rowbase + q - NMETA) * 1536 + h * 128 + c * 64 + hi * 8;
; #pragma unroll
;       for (int d0 = 0; d0 < 4; ++d0) qr[d0] = *(const bf16x8*)(qp + d0 * 16); }
;     const bf16_t* kg[2]; const bf16_t* vg[2];
; #pragma unroll
;     for (int i = 0; i < 2; ++i) { const int row = 4 * (i * 8 + w) + (lane >> 4), kch = (lane & 15) ^ (row & 15);
;         kg[i] = U3 + (size_t)row * 1536 + 512 + h * 128 + kch * 8;
;         const int rp = row, p = (lane & 15) ^ (rp & 15), dv = 2 * rp + (p >> 3), ch = p & 7;
;         vg[i] = VT + (size_t)(h * 128 + dv) * MPAD + ch * 8; }
;     ...
;     const int pi = (r32 & 0x13) | ((r32 & 4) << 1) | ((r32 & 8) >> 1);
;     unsigned koff[4], voff[4];
; #pragma unroll
;     for (int d0 = 0; d0 < 4; ++d0) koff[d0] = pi * 256 + (((c * 8 + d0 * 2 + hi) ^ (pi & 15)) << 4);
; #pragma unroll
;     for (int j = 0; j < 4; ++j) voff[j] = 16384 + (r32 >> 1) * 256 + (((((r32 & 1) << 3) + 2 * j + hi) ^ (r32 >> 1)) << 4);
;     ATT_DMA(0, 0); ATT_DMA(1, 1);
;     asm volatile("s_waitcnt vmcnt(4)" ::: "memory");
;     asm volatile("s_waitcnt lgkmcnt(0)" ::: "memory"); __builtin_amdgcn_s_barrier(); asm volatile("" ::: "memory");
;     const float bL = lut[0], bR = lut[256];
;     f32x16 o[4];
; #pragma unroll
;     for (int d0 = 0; d0 < 4; ++d0)
; #pragma unroll
;         for (int r = 0; r < 16; ++r) o[d0][r] = 0.f;
;     float mhat = 0.f, l = 0.f;
;     bf16x8 pf[4];
; #pragma unroll
;     for (int j = 0; j < 4; ++j) pf[j] = (bf16x8){0, 0, 0, 0, 0, 0, 0, 0};
;     int slot = 0, slotp = 0, slot2 = 2;
.Latt_lutskip:
	s_lshl_b32 s12, s17, 13
	s_ashr_i32 s14, s73, 6
	s_ashr_i32 s74, s73, 8
	s_add_i32 s12, s12, 0x8000
	s_lshl_b32 s13, s17, 11
	s_and_b64 s[10:11], exec, s[10:11]
	s_cselect_b32 s10, s13, s12
	s_and_b32 s72, s14, 3
	s_lshl_b32 s11, s16, 7
	s_lshl_b32 s12, s72, 5
	s_or_b32 s76, s12, s11
	v_and_b32_e32 v158, 31, v155
	s_or_b32 s62, s76, 16
	v_add_u32_e32 v168, s62, v158
	s_add_i32 s63, s10, -16
	v_add_u32_e32 v2, s63, v168
	v_mov_b64_e32 v[0:1], s[20:21]
	v_mad_i64_i32 v[2:3], s[12:13], v2, s69, v[0:1]
	s_lshl_b32 s12, s74, 6
	v_bfe_u32 v159, v155, 5, 1
	s_ashr_i32 s13, s12, 31
	s_lshl_b32 s11, s14, 2
	v_bfe_u32 v156, v155, 4, 2
	v_lshl_add_u64 v[2:3], s[12:13], 1, v[2:3]
	v_lshlrev_b32_e32 v160, 4, v159
	v_or_b32_e32 v8, s11, v156
	v_lshl_add_u64 v[2:3], v[2:3], 0, v[160:161]
	v_bitop3_b32 v4, v8, 15, v155 bitop3:0x48
	global_load_dwordx4 v[112:115], v[2:3], off
	global_load_dwordx4 v[116:119], v[2:3], off offset:32
	global_load_dwordx4 v[120:123], v[2:3], off offset:64
	global_load_dwordx4 v[124:127], v[2:3], off offset:96
	v_bitop3_b32 v6, s11, v155, v156 bitop3:0x36
	v_mad_i64_i32 v[2:3], s[12:13], v8, s69, v[0:1]
	v_lshlrev_b32_e32 v4, 4, v4
	v_mov_b32_e32 v5, v161
	v_lshl_add_u64 v[146:147], v[2:3], 0, v[4:5]
	v_bfe_u32 v2, v6, 3, 1
	v_lshl_add_u32 v3, v8, 1, s37
	v_or_b32_e32 v4, v2, v3
	v_mov_b64_e32 v[2:3], s[52:53]
	v_lshlrev_b32_e32 v6, 4, v6
	v_mad_i64_i32 v[4:5], s[12:13], v4, s41, v[2:3]
	v_and_b32_e32 v6, 0x70, v6
	v_mov_b32_e32 v7, v161
	v_lshl_add_u64 v[148:149], v[4:5], 0, v[6:7]
	v_add_u32_e32 v6, 32, v8
	v_bitop3_b32 v4, v6, 15, v155 bitop3:0x48
	v_xor_b32_e32 v7, v6, v155
	v_mad_i64_i32 v[0:1], s[12:13], v6, s69, v[0:1]
	v_lshlrev_b32_e32 v4, 4, v4
	v_mov_b32_e32 v5, v161
	v_lshl_add_u64 v[150:151], v[0:1], 0, v[4:5]
	v_bfe_u32 v0, v7, 3, 1
	v_lshl_add_u32 v1, v6, 1, s37
	v_or_b32_e32 v0, v0, v1
	v_mad_i64_i32 v[0:1], s[12:13], v0, s41, v[2:3]
	v_lshlrev_b32_e32 v2, 4, v7
	v_and_b32_e32 v2, 0x70, v2
	v_mov_b32_e32 v3, v161
	s_lshl_b32 s11, s14, 10
	v_lshl_add_u64 v[152:153], v[0:1], 0, v[2:3]
	s_add_i32 s77, s11, 0
	v_mad_i64_i32 v[0:1], s[12:13], s10, v212, v[146:147]
	v_lshl_add_u64 v[0:1], v[0:1], 0, s[86:87]
	s_mov_b32 m0, s77
	s_ashr_i32 s11, s10, 31
	global_load_lds_dwordx4 v[0:1], off
	v_mad_i64_i32 v[0:1], s[12:13], s10, v212, v[150:151]
	v_lshl_add_u64 v[0:1], v[0:1], 0, s[86:87]
	s_add_i32 m0, s77, 0x2000
	s_lshl_b64 s[12:13], s[10:11], 1
	global_load_lds_dwordx4 v[0:1], off
	v_lshl_add_u64 v[0:1], v[148:149], 0, s[12:13]
	s_add_i32 m0, s77, 0x4000
	s_or_b32 s11, s10, 64
	global_load_lds_dwordx4 v[0:1], off
	v_lshl_add_u64 v[2:3], v[152:153], 0, s[12:13]
	s_add_i32 m0, s77, 0x6000
	v_mad_i64_i32 v[4:5], s[12:13], s11, v212, v[146:147]
	global_load_lds_dwordx4 v[2:3], off
	s_add_i32 m0, s77, 0x8000
	v_lshl_add_u64 v[4:5], v[4:5], 0, s[86:87]
	global_load_lds_dwordx4 v[4:5], off
	v_mad_i64_i32 v[4:5], s[12:13], s11, v212, v[150:151]
	v_lshl_add_u64 v[4:5], v[4:5], 0, s[86:87]
	s_add_i32 m0, s77, 0xa000
	v_lshl_add_u64 v[0:1], v[0:1], 0, s[90:91]
	global_load_lds_dwordx4 v[4:5], off
	s_add_i32 m0, s77, 0xc000
	s_add_i32 s79, 0, 0x20000
	global_load_lds_dwordx4 v[0:1], off
	v_lshl_add_u64 v[0:1], v[2:3], 0, s[90:91]
	s_add_i32 m0, s77, 0xe000
	v_lshl_or_b32 v3, s74, 3, v159
	global_load_lds_dwordx4 v[0:1], off
	v_subrev_u32_e32 v146, s20, v146
	v_subrev_u32_e32 v150, s20, v150
	v_subrev_u32_e32 v148, s52, v148
	v_subrev_u32_e32 v152, s52, v152
	v_and_b32_e32 v0, 19, v155
	v_lshlrev_b32_e32 v1, 1, v155
	v_and_or_b32 v0, v1, 8, v0
	v_lshrrev_b32_e32 v1, 1, v155
	v_and_b32_e32 v1, 4, v1
	v_or_b32_e32 v2, v0, v1
	v_bitop3_b32 v0, v0, 15, v1 bitop3:0xc8
	v_bitop3_b32 v1, v2, v3, 15 bitop3:0x6c
	v_lshlrev_b32_e32 v171, 8, v2
	v_lshlrev_b32_e32 v173, 4, v1
	v_bitop3_b32 v1, v3, v0, 2 bitop3:0x36
	v_lshlrev_b32_e32 v2, 3, v155
	v_lshlrev_b32_e32 v174, 4, v1
	v_bitop3_b32 v1, v3, v0, 4 bitop3:0x36
	v_bitop3_b32 v0, v3, v0, 6 bitop3:0x36
	v_and_b32_e32 v2, 8, v2
	v_lshlrev_b32_e32 v176, 4, v0
	v_bfe_u32 v0, v155, 1, 4
	v_or_b32_e32 v3, v2, v159
	s_waitcnt vmcnt(4)
	v_lshlrev_b32_e32 v175, 4, v1
	v_lshlrev_b32_e32 v1, 8, v0
	v_bitop3_b32 v2, v2, v0, v159 bitop3:0x36
	v_bitop3_b32 v4, v3, v0, 2 bitop3:0x36
	v_bitop3_b32 v5, v3, v0, 4 bitop3:0x36
	v_bitop3_b32 v0, v3, v0, 6 bitop3:0x36
	s_waitcnt lgkmcnt(0)
	s_barrier
	v_mov_b32_e32 v3, s79
	v_mov_b32_e32 v6, s50
	ds_read_b32 v178, v3 offset:640
	ds_read_b32 v180, v6 offset:640
	v_mov_b32_e32 v48, v161
	v_mov_b32_e32 v49, v161
	v_mov_b32_e32 v140, v161
	v_mov_b32_e32 v141, v161
	v_lshl_or_b32 v179, v2, 4, v1
	v_lshl_or_b32 v177, v4, 4, v1
	v_lshl_or_b32 v172, v5, 4, v1
	v_lshl_or_b32 v170, v0, 4, v1
	s_lshl_b32 s85, s75, 6
	v_mov_b32_e32 v50, v161
	v_mov_b32_e32 v51, v161
	v_mov_b32_e32 v52, v161
	v_mov_b32_e32 v53, v161
	v_mov_b32_e32 v54, v161
	v_mov_b32_e32 v55, v161
	v_mov_b32_e32 v56, v161
	v_mov_b32_e32 v57, v161
	v_mov_b32_e32 v58, v161
	v_mov_b32_e32 v59, v161
	v_mov_b32_e32 v60, v161
	v_mov_b32_e32 v61, v161
	v_mov_b32_e32 v62, v161
	v_mov_b32_e32 v63, v161
	v_mov_b32_e32 v142, v161
	v_mov_b32_e32 v143, v161
	v_mov_b64_e32 v[136:137], v[140:141]
	v_mov_b64_e32 v[132:133], v[140:141]
	v_mov_b64_e32 v[128:129], v[140:141]
	v_mov_b64_e32 v[32:33], v[48:49]
	v_mov_b64_e32 v[16:17], v[48:49]
	v_mov_b64_e32 v[0:1], v[48:49]
	v_lshlrev_b32_e32 v157, 3, v159
	s_mov_b32 s78, 2
	s_or_b32 s84, s10, 0x80
	s_add_i32 s97, s85, 64
	s_mov_b32 s33, 0
	v_mov_b32_e32 v169, 0
	v_mov_b64_e32 v[138:139], v[142:143]
	v_mov_b64_e32 v[134:135], v[142:143]
	v_mov_b64_e32 v[130:131], v[142:143]
	v_mov_b64_e32 v[34:35], v[50:51]
	v_mov_b64_e32 v[36:37], v[52:53]
	v_mov_b64_e32 v[38:39], v[54:55]
	v_mov_b64_e32 v[40:41], v[56:57]
	v_mov_b64_e32 v[42:43], v[58:59]
	v_mov_b64_e32 v[44:45], v[60:61]
	v_mov_b64_e32 v[46:47], v[62:63]
	v_mov_b64_e32 v[18:19], v[50:51]
	v_mov_b64_e32 v[20:21], v[52:53]
	v_mov_b64_e32 v[22:23], v[54:55]
	v_mov_b64_e32 v[24:25], v[56:57]
	v_mov_b64_e32 v[26:27], v[58:59]
	v_mov_b64_e32 v[28:29], v[60:61]
	v_mov_b64_e32 v[30:31], v[62:63]
	v_mov_b64_e32 v[2:3], v[50:51]
	v_mov_b64_e32 v[4:5], v[52:53]
	v_mov_b64_e32 v[6:7], v[54:55]
	v_mov_b64_e32 v[8:9], v[56:57]
	v_mov_b64_e32 v[10:11], v[58:59]
	v_mov_b64_e32 v[12:13], v[60:61]
	v_mov_b64_e32 v[14:15], v[62:63]
	v_mov_b32_e32 v181, 0
	s_mov_b32 s10, 0
	s_mov_b32 s16, 0
	s_mov_b32 s45, 2
	s_mov_b32 s99, -1
	s_waitcnt vmcnt(0) lgkmcnt(0)

; #define LAS __attribute__((address_space(3)))
; #define SBAR() __builtin_amdgcn_sched_barrier(0)
; #define VRD(J) do { _Pragma("unroll") for (int d0_ = 0; d0_ < 4; ++d0_) vf[(J) & 1][d0_] = *(const LAS bf16x8*)(pbuf + voff[J] + d0_ * 4096); } while (0)
; #define PVM(J, D0) do { __builtin_amdgcn_s_setprio(1); o[D0] = __builtin_amdgcn_mfma_f32_32x32x16_bf16(vf[(J) & 1][D0], pf[J], o[D0], 0, 0, 0); __builtin_amdgcn_s_setprio(0); } while (0)
; __device__ __forceinline__ void attn_unit(LAS unsigned char* lds, const bf16_t* __restrict__ U3, const bf16_t* __restrict__ VT, bf16_t* __restrict__ MIX, ...
;     ...
;     {
;         LAS unsigned char* pbuf = lds + slotp * STAGE; bf16x8 vf[2][4];
;         VRD(0);
; #pragma unroll
;         for (int j = 0; j < 4; ++j) { if (j < 3) VRD((j + 1) & 3); SBAR();
; #pragma unroll
;             for (int d0 = 0; d0 < 4; ++d0) PVM(j, d0);
;             SBAR(); }
;     }
;     asm volatile("s_waitcnt lgkmcnt(0)" ::: "memory"); __builtin_amdgcn_s_barrier(); asm volatile("" ::: "memory");
;     ...
;     l += __shfl_xor(l, 32);
;     const float inv = 1.0f / l;
;     LAS float* comb = (LAS float*)(lds + LDS_COMB) + (w & 3) * 4096 + r32;
;     if (c == 1) { const float sc = lam * inv;
;     ...
;                 for (int rg = 0; rg < 4; ++rg) { const int dv = 32 * d0 + 8 * rg; const f32x4 gn = *(const f32x4*)(gain + dv + 4 * hi);
.LBB0_537:
	s_and_saveexec_b64 s[10:11], s[6:7]
	s_cbranch_execz .Latt_prepop_done
	v_mov_b32_e32 v183, 1
	global_atomic_add v183, v161, v183, s[18:19] sc0
.Latt_prepop_done:
	s_or_b64 exec, exec, s[10:11]
	s_mov_b32 s101, 1
	global_load_dwordx4 v[96:99], v160, s[94:95]
	global_load_dwordx4 v[100:103], v160, s[94:95] offset:32
	global_load_dwordx4 v[104:107], v160, s[94:95] offset:64
	global_load_dwordx4 v[108:111], v160, s[94:95] offset:96
	global_load_dwordx4 v[112:115], v160, s[94:95] offset:128
	global_load_dwordx4 v[116:119], v160, s[94:95] offset:160
	global_load_dwordx4 v[120:123], v160, s[94:95] offset:192
	global_load_dwordx4 v[124:127], v160, s[94:95] offset:224
	global_load_dwordx4 v[218:221], v160, s[94:95] offset:256
	global_load_dwordx4 v[222:225], v160, s[94:95] offset:288
	global_load_dwordx4 v[226:229], v160, s[94:95] offset:320
	global_load_dwordx4 v[230:233], v160, s[94:95] offset:352
	global_load_dwordx4 v[234:237], v160, s[94:95] offset:384
	global_load_dwordx4 v[238:241], v160, s[94:95] offset:416
	global_load_dwordx4 v[242:245], v160, s[94:95] offset:448
	global_load_dwordx4 v[246:249], v160, s[94:95] offset:480
	v_add_u32_e32 v76, s43, v179
	v_add_u32_e32 v92, s43, v177
	ds_read_b128 v[64:67], v76 offset:16384
	ds_read_b128 v[68:71], v76 offset:20480
	ds_read_b128 v[72:75], v76 offset:24576
	ds_read_b128 v[76:79], v76 offset:28672
	ds_read_b128 v[80:83], v92 offset:16384
	ds_read_b128 v[84:87], v92 offset:20480
	ds_read_b128 v[88:91], v92 offset:24576
	ds_read_b128 v[92:95], v92 offset:28672
	s_setprio 1
	s_waitcnt lgkmcnt(0)
	v_mfma_f32_32x32x16_bf16 v[48:63], v[64:67], v[140:143], v[48:63]
	s_setprio 0
	s_setprio 1
	v_mfma_f32_32x32x16_bf16 v[32:47], v[68:71], v[140:143], v[32:47]
	s_setprio 0
	s_setprio 1
	v_mfma_f32_32x32x16_bf16 v[16:31], v[72:75], v[140:143], v[16:31]
	s_setprio 0
	s_setprio 1
	v_mfma_f32_32x32x16_bf16 v[0:15], v[76:79], v[140:143], v[0:15]
	s_setprio 0
	v_add_u32_e32 v76, s43, v172
	ds_read_b128 v[64:67], v76 offset:16384
	ds_read_b128 v[68:71], v76 offset:20480
	ds_read_b128 v[72:75], v76 offset:24576
	ds_read_b128 v[76:79], v76 offset:28672
	s_setprio 1
	v_mfma_f32_32x32x16_bf16 v[48:63], v[80:83], v[136:139], v[48:63]
	s_setprio 0
	s_setprio 1
	v_mfma_f32_32x32x16_bf16 v[32:47], v[84:87], v[136:139], v[32:47]
	s_setprio 0
	s_setprio 1
	v_mfma_f32_32x32x16_bf16 v[16:31], v[88:91], v[136:139], v[16:31]
	s_setprio 0
	s_setprio 1
	v_mfma_f32_32x32x16_bf16 v[0:15], v[92:95], v[136:139], v[0:15]
	s_setprio 0
	v_add_u32_e32 v92, s43, v170
	ds_read_b128 v[80:83], v92 offset:16384
	ds_read_b128 v[84:87], v92 offset:20480
	ds_read_b128 v[88:91], v92 offset:24576
	ds_read_b128 v[92:95], v92 offset:28672
	s_setprio 1
	s_waitcnt lgkmcnt(0)
	v_mfma_f32_32x32x16_bf16 v[48:63], v[64:67], v[132:135], v[48:63]
	s_setprio 0
	s_setprio 1
	v_mfma_f32_32x32x16_bf16 v[32:47], v[68:71], v[132:135], v[32:47]
	s_setprio 0
	s_setprio 1
	v_mfma_f32_32x32x16_bf16 v[16:31], v[72:75], v[132:135], v[16:31]
	s_setprio 0
	s_setprio 1
	v_mfma_f32_32x32x16_bf16 v[0:15], v[76:79], v[132:135], v[0:15]
	s_setprio 0
	s_setprio 1
	v_mfma_f32_32x32x16_bf16 v[48:63], v[80:83], v[128:131], v[48:63]
	s_setprio 0
	s_setprio 1
	v_mfma_f32_32x32x16_bf16 v[32:47], v[84:87], v[128:131], v[32:47]
	s_setprio 0
	s_setprio 1
	v_mfma_f32_32x32x16_bf16 v[16:31], v[88:91], v[128:131], v[16:31]
	s_setprio 0
	s_setprio 1
	v_mfma_f32_32x32x16_bf16 v[0:15], v[92:95], v[128:131], v[0:15]
	s_setprio 0
	ds_bpermute_b32 v64, v145, v169
	s_waitcnt lgkmcnt(0)
	s_barrier
	s_waitcnt lgkmcnt(0)
	v_add_f32_e32 v64, v169, v64
	v_div_scale_f32 v65, s[10:11], v64, v64, 1.0
	v_rcp_f32_e32 v66, v65
	v_div_scale_f32 v67, vcc, 1.0, v64, 1.0
	s_lshl_b32 s10, s72, 14
	v_fma_f32 v68, -v65, v66, 1.0
	v_fmac_f32_e32 v66, v68, v66
	v_mul_f32_e32 v68, v67, v66
	v_fma_f32 v69, -v65, v68, v67
	v_fmac_f32_e32 v68, v69, v66
	v_fma_f32 v65, -v65, v68, v67
	v_div_fmas_f32 v65, v65, v66, v68
	s_add_i32 s10, s10, 0
	v_div_fixup_f32 v64, v65, v64, 1.0
	v_lshl_add_u32 v65, v158, 2, s10
	v_lshl_add_u32 v77, v159, 9, v65
	s_cmp_eq_u32 s74, 1
	v_add_u32_e32 v76, 0x400, v77
	v_add_u32_e32 v67, 0x800, v77
	v_add_u32_e32 v75, 0xc00, v77
	v_add_u32_e32 v74, 0x1000, v77
	v_add_u32_e32 v68, 0x1400, v77
	v_add_u32_e32 v69, 0x1800, v77
	v_add_u32_e32 v71, 0x1c00, v77
	v_add_u32_e32 v73, 0x2000, v77
	v_add_u32_e32 v72, 0x2400, v77
	v_add_u32_e32 v70, 0x2800, v77
	v_add_u32_e32 v82, 0x2c00, v77
	v_add_u32_e32 v81, 0x3000, v77
	v_add_u32_e32 v80, 0x3400, v77
	v_add_u32_e32 v79, 0x3800, v77
	v_add_u32_e32 v78, 0x3c00, v77
	s_cbranch_scc0 .LBB0_539
; __device__ __forceinline__ void attn_unit(LAS unsigned char* lds, const bf16_t* __restrict__ U3, const bf16_t* __restrict__ VT, bf16_t* __restrict__ MIX, ...
;     ...
;     if (c == 1) { const float sc = lam * inv;
; #pragma unroll
;         for (int d0 = 0; d0 < 4; ++d0)
; #pragma unroll
;             for (int r = 0; r < 16; ++r) comb[(32 * d0 + (r & 3) + 8 * (r >> 2) + 4 * hi) * 32] = o[d0][r] * sc; }
;     __syncthreads();
;     if (c == 0) { float ss = 0.f;
; #pragma unroll
;         for (int d0 = 0; d0 < 4; ++d0)
; #pragma unroll
;             for (int r = 0; r < 16; ++r) { const float v = o[d0][r] * inv - comb[(32 * d0 + (r & 3) + 8 * (r >> 2) + 4 * hi) * 32]; o[d0][r] = v; ss += v * v; }
	v_mul_f32_e32 v65, v154, v64
	v_mul_f32_e32 v66, v48, v65
	v_mul_f32_e32 v83, v49, v65
	ds_write2_b32 v77, v66, v83 offset1:32
	v_mul_f32_e32 v66, v50, v65
	v_mul_f32_e32 v83, v51, v65
	ds_write2_b32 v77, v66, v83 offset0:64 offset1:96
	v_mul_f32_e32 v66, v52, v65
	v_mul_f32_e32 v83, v53, v65
	ds_write2_b32 v76, v66, v83 offset1:32
	v_mul_f32_e32 v66, v54, v65
	v_mul_f32_e32 v83, v55, v65
	ds_write2_b32 v76, v66, v83 offset0:64 offset1:96
	v_mul_f32_e32 v66, v56, v65
	v_mul_f32_e32 v83, v57, v65
	ds_write2_b32 v67, v66, v83 offset1:32
	v_mul_f32_e32 v66, v58, v65
	v_mul_f32_e32 v83, v59, v65
	ds_write2_b32 v67, v66, v83 offset0:64 offset1:96
	v_mul_f32_e32 v66, v60, v65
	v_mul_f32_e32 v83, v61, v65
	ds_write2_b32 v75, v66, v83 offset1:32
	v_mul_f32_e32 v66, v62, v65
	v_mul_f32_e32 v83, v63, v65
	ds_write2_b32 v75, v66, v83 offset0:64 offset1:96
	v_mul_f32_e32 v66, v32, v65
	v_mul_f32_e32 v83, v33, v65
	ds_write2_b32 v74, v66, v83 offset1:32
	v_mul_f32_e32 v66, v34, v65
	v_mul_f32_e32 v83, v35, v65
	ds_write2_b32 v74, v66, v83 offset0:64 offset1:96
	v_mul_f32_e32 v66, v36, v65
	v_mul_f32_e32 v83, v37, v65
	ds_write2_b32 v68, v66, v83 offset1:32
	v_mul_f32_e32 v66, v38, v65
	v_mul_f32_e32 v83, v39, v65
	ds_write2_b32 v68, v66, v83 offset0:64 offset1:96
	v_mul_f32_e32 v66, v40, v65
	v_mul_f32_e32 v83, v41, v65
	ds_write2_b32 v69, v66, v83 offset1:32
	v_mul_f32_e32 v66, v42, v65
	v_mul_f32_e32 v83, v43, v65
	ds_write2_b32 v69, v66, v83 offset0:64 offset1:96
	v_mul_f32_e32 v66, v44, v65
	v_mul_f32_e32 v83, v45, v65
	ds_write2_b32 v71, v66, v83 offset1:32
	v_mul_f32_e32 v66, v46, v65
	v_mul_f32_e32 v83, v47, v65
	ds_write2_b32 v71, v66, v83 offset0:64 offset1:96
	v_mul_f32_e32 v66, v16, v65
	v_mul_f32_e32 v83, v17, v65
	ds_write2_b32 v73, v66, v83 offset1:32
	v_mul_f32_e32 v66, v18, v65
	v_mul_f32_e32 v83, v19, v65
	ds_write2_b32 v73, v66, v83 offset0:64 offset1:96
	v_mul_f32_e32 v66, v20, v65
	v_mul_f32_e32 v83, v21, v65
	ds_write2_b32 v72, v66, v83 offset1:32
	v_mul_f32_e32 v66, v22, v65
	v_mul_f32_e32 v83, v23, v65
	ds_write2_b32 v72, v66, v83 offset0:64 offset1:96
	v_mul_f32_e32 v66, v24, v65
	v_mul_f32_e32 v83, v25, v65
	ds_write2_b32 v70, v66, v83 offset1:32
	v_mul_f32_e32 v66, v26, v65
	v_mul_f32_e32 v83, v27, v65
	ds_write2_b32 v70, v66, v83 offset0:64 offset1:96
	v_mul_f32_e32 v66, v28, v65
	v_mul_f32_e32 v83, v29, v65
	ds_write2_b32 v82, v66, v83 offset1:32
	v_mul_f32_e32 v66, v30, v65
	v_mul_f32_e32 v83, v31, v65
	ds_write2_b32 v82, v66, v83 offset0:64 offset1:96
	v_mul_f32_e32 v66, v0, v65
	v_mul_f32_e32 v83, v1, v65
	ds_write2_b32 v81, v66, v83 offset1:32
	v_mul_f32_e32 v66, v2, v65
	v_mul_f32_e32 v83, v3, v65
	ds_write2_b32 v81, v66, v83 offset0:64 offset1:96
	v_mul_f32_e32 v66, v4, v65
	v_mul_f32_e32 v83, v5, v65
	ds_write2_b32 v80, v66, v83 offset1:32
	v_mul_f32_e32 v66, v6, v65
	v_mul_f32_e32 v83, v7, v65
	ds_write2_b32 v80, v66, v83 offset0:64 offset1:96
	v_mul_f32_e32 v66, v8, v65
	v_mul_f32_e32 v83, v9, v65
	ds_write2_b32 v79, v66, v83 offset1:32
	v_mul_f32_e32 v66, v10, v65
	v_mul_f32_e32 v83, v11, v65
	ds_write2_b32 v79, v66, v83 offset0:64 offset1:96
	v_mul_f32_e32 v66, v12, v65
	v_mul_f32_e32 v83, v13, v65
	ds_write2_b32 v78, v66, v83 offset1:32
	v_mul_f32_e32 v66, v14, v65
	v_mul_f32_e32 v65, v15, v65
	ds_write2_b32 v78, v66, v65 offset0:64 offset1:96
.LBB0_539:
	s_cmpk_gt_u32 s73, 0xff
	s_waitcnt vmcnt(0) lgkmcnt(0)
	s_barrier
	s_cbranch_scc1 .LBB0_498
	ds_read2_b32 v[128:129], v77 offset1:32
	ds_read2_b32 v[130:131], v77 offset0:64 offset1:96
	ds_read2_b32 v[132:133], v76 offset1:32
	ds_read2_b32 v[134:135], v76 offset0:64 offset1:96
	ds_read2_b32 v[136:137], v67 offset1:32
	ds_read2_b32 v[138:139], v67 offset0:64 offset1:96
	ds_read2_b32 v[140:141], v75 offset1:32
	ds_read2_b32 v[142:143], v75 offset0:64 offset1:96
	ds_read2_b32 v[186:187], v74 offset1:32
	ds_read2_b32 v[188:189], v74 offset0:64 offset1:96
	ds_read2_b32 v[190:191], v68 offset1:32
	ds_read2_b32 v[192:193], v68 offset0:64 offset1:96
	ds_read2_b32 v[194:195], v69 offset1:32
	ds_read2_b32 v[196:197], v69 offset0:64 offset1:96
	ds_read2_b32 v[198:199], v71 offset1:32
	ds_read2_b32 v[200:201], v71 offset0:64 offset1:96
	s_waitcnt lgkmcnt(0)
	s_mulk_i32 s72, 0x2200
	s_add_i32 s10, s72, 0
	s_add_i32 s10, s10, 0x10000
	s_waitcnt lgkmcnt(0)
	v_fma_f32 v66, v48, v64, -v128
	v_fma_f32 v65, v49, v64, -v129
	v_mul_f32_e32 v83, v65, v65
	v_fmac_f32_e32 v83, v66, v66
	s_waitcnt lgkmcnt(0)
	v_fma_f32 v50, v50, v64, -v130
	v_fma_f32 v51, v51, v64, -v131
	v_fmac_f32_e32 v83, v50, v50
	v_fmac_f32_e32 v83, v51, v51
	s_waitcnt lgkmcnt(0)
	v_fma_f32 v48, v52, v64, -v132
	v_fma_f32 v49, v53, v64, -v133
	v_fmac_f32_e32 v83, v48, v48
	v_fmac_f32_e32 v83, v49, v49
	s_waitcnt lgkmcnt(1)
	v_fma_f32 v52, v54, v64, -v134
	v_fma_f32 v53, v55, v64, -v135
	s_waitcnt lgkmcnt(0)
	v_fma_f32 v55, v56, v64, -v136
	v_fma_f32 v54, v57, v64, -v137
	v_fmac_f32_e32 v83, v52, v52
	v_fmac_f32_e32 v83, v53, v53
	v_fmac_f32_e32 v83, v55, v55
	s_waitcnt lgkmcnt(1)
	v_fma_f32 v67, v58, v64, -v138
	v_fma_f32 v58, v59, v64, -v139
	s_waitcnt lgkmcnt(0)
	v_fma_f32 v57, v60, v64, -v140
	v_fma_f32 v56, v61, v64, -v141
	v_fmac_f32_e32 v83, v54, v54
	v_fmac_f32_e32 v83, v67, v67
	v_fmac_f32_e32 v83, v58, v58
	v_fmac_f32_e32 v83, v57, v57
	s_waitcnt lgkmcnt(0)
	v_fma_f32 v61, v62, v64, -v142
	v_fma_f32 v60, v63, v64, -v143
	v_fmac_f32_e32 v83, v56, v56
	v_fmac_f32_e32 v83, v61, v61
	v_fmac_f32_e32 v83, v60, v60
	s_waitcnt lgkmcnt(1)
	v_fma_f32 v59, v32, v64, -v186
	v_fma_f32 v32, v33, v64, -v187
	s_waitcnt lgkmcnt(0)
; __device__ __forceinline__ void attn_unit(LAS unsigned char* lds, const bf16_t* __restrict__ U3, const bf16_t* __restrict__ VT, bf16_t* __restrict__ MIX, ...
;     ...
;     if (c == 0) { float ss = 0.f;
; #pragma unroll
;         for (int d0 = 0; d0 < 4; ++d0)
; #pragma unroll
;             for (int r = 0; r < 16; ++r) { const float v = o[d0][r] * inv - comb[(32 * d0 + (r & 3) + 8 * (r >> 2) + 4 * hi) * 32]; o[d0][r] = v; ss += v * v; }
;         ss += __shfl_xor(ss, 32);
	v_fma_f32 v63, v34, v64, -v188
	v_fma_f32 v62, v35, v64, -v189
	v_fmac_f32_e32 v83, v59, v59
	v_fmac_f32_e32 v83, v32, v32
	v_fmac_f32_e32 v83, v63, v63
	v_fmac_f32_e32 v83, v62, v62
	s_waitcnt lgkmcnt(0)
	v_fma_f32 v34, v36, v64, -v190
	v_fma_f32 v33, v37, v64, -v191
	v_fmac_f32_e32 v83, v34, v34
	v_fmac_f32_e32 v83, v33, v33
	s_waitcnt lgkmcnt(0)
	v_fma_f32 v68, v38, v64, -v192
	v_fma_f32 v38, v39, v64, -v193
	v_fmac_f32_e32 v83, v68, v68
	v_fmac_f32_e32 v83, v38, v38
	s_waitcnt lgkmcnt(0)
	v_fma_f32 v36, v40, v64, -v194
	v_fma_f32 v35, v41, v64, -v195
	v_fmac_f32_e32 v83, v36, v36
	v_fmac_f32_e32 v83, v35, v35
	s_waitcnt lgkmcnt(0)
	v_fma_f32 v69, v42, v64, -v196
	v_fma_f32 v42, v43, v64, -v197
	v_fmac_f32_e32 v83, v69, v69
	v_fmac_f32_e32 v83, v42, v42
	s_waitcnt lgkmcnt(0)
	v_fma_f32 v39, v44, v64, -v198
	v_fma_f32 v37, v45, v64, -v199
	v_fmac_f32_e32 v83, v39, v39
	v_fmac_f32_e32 v83, v37, v37
	s_waitcnt lgkmcnt(0)
	v_fma_f32 v71, v46, v64, -v200
	v_fma_f32 v46, v47, v64, -v201
	ds_read2_b32 v[128:129], v73 offset1:32
	ds_read2_b32 v[130:131], v73 offset0:64 offset1:96
	ds_read2_b32 v[132:133], v72 offset1:32
	ds_read2_b32 v[134:135], v72 offset0:64 offset1:96
	ds_read2_b32 v[136:137], v70 offset1:32
	ds_read2_b32 v[138:139], v70 offset0:64 offset1:96
	ds_read2_b32 v[140:141], v82 offset1:32
	ds_read2_b32 v[142:143], v82 offset0:64 offset1:96
	ds_read2_b32 v[186:187], v81 offset1:32
	ds_read2_b32 v[188:189], v81 offset0:64 offset1:96
	ds_read2_b32 v[190:191], v80 offset1:32
	ds_read2_b32 v[192:193], v80 offset0:64 offset1:96
	ds_read2_b32 v[194:195], v79 offset1:32
	ds_read2_b32 v[196:197], v79 offset0:64 offset1:96
	ds_read2_b32 v[198:199], v78 offset1:32
	ds_read2_b32 v[200:201], v78 offset0:64 offset1:96
	s_waitcnt lgkmcnt(0)
	v_fmac_f32_e32 v83, v71, v71
	v_fmac_f32_e32 v83, v46, v46
	s_waitcnt lgkmcnt(0)
	v_fma_f32 v43, v16, v64, -v128
	v_fma_f32 v41, v17, v64, -v129
	v_fmac_f32_e32 v83, v43, v43
	v_fmac_f32_e32 v83, v41, v41
	s_waitcnt lgkmcnt(0)
	v_fma_f32 v75, v18, v64, -v130
	v_fma_f32 v74, v19, v64, -v131
	v_fmac_f32_e32 v83, v75, v75
	v_fmac_f32_e32 v83, v74, v74
	s_waitcnt lgkmcnt(0)
	v_fma_f32 v47, v20, v64, -v132
	v_fma_f32 v44, v21, v64, -v133
	v_fmac_f32_e32 v83, v47, v47
	v_fmac_f32_e32 v83, v44, v44
	s_waitcnt lgkmcnt(0)
	v_fma_f32 v77, v22, v64, -v134
	v_fma_f32 v76, v23, v64, -v135
	v_fmac_f32_e32 v83, v77, v77
	v_fmac_f32_e32 v83, v76, v76
	s_waitcnt lgkmcnt(0)
	v_fma_f32 v73, v24, v64, -v136
	v_fma_f32 v72, v25, v64, -v137
	v_fmac_f32_e32 v83, v73, v73
	v_fmac_f32_e32 v83, v72, v72
	s_waitcnt lgkmcnt(0)
	v_fma_f32 v70, v26, v64, -v138
	v_fma_f32 v45, v27, v64, -v139
	v_fmac_f32_e32 v83, v70, v70
	v_fmac_f32_e32 v83, v45, v45
	s_waitcnt lgkmcnt(0)
	v_fma_f32 v40, v28, v64, -v140
	v_fma_f32 v28, v29, v64, -v141
	v_fmac_f32_e32 v83, v40, v40
	v_fmac_f32_e32 v83, v28, v28
	s_waitcnt lgkmcnt(0)
	v_fma_f32 v27, v30, v64, -v142
	v_fma_f32 v26, v31, v64, -v143
	v_fmac_f32_e32 v83, v27, v27
	v_fmac_f32_e32 v83, v26, v26
	s_waitcnt lgkmcnt(0)
	v_fma_f32 v25, v0, v64, -v186
	v_fma_f32 v24, v1, v64, -v187
	v_fmac_f32_e32 v83, v25, v25
	v_fmac_f32_e32 v83, v24, v24
	s_waitcnt lgkmcnt(0)
	v_fma_f32 v23, v2, v64, -v188
	v_fma_f32 v22, v3, v64, -v189
	v_fmac_f32_e32 v83, v23, v23
	v_fmac_f32_e32 v83, v22, v22
	s_waitcnt lgkmcnt(0)
	v_fma_f32 v21, v4, v64, -v190
	v_fma_f32 v20, v5, v64, -v191
	v_fmac_f32_e32 v83, v21, v21
	v_fmac_f32_e32 v83, v20, v20
	s_waitcnt lgkmcnt(0)
	v_pk_fma_f32 v[18:19], v[6:7], v[64:65], v[192:193] op_sel_hi:[1,0,1] neg_lo:[0,0,1] neg_hi:[0,0,1]
	s_nop 0
	v_pk_mul_f32 v[0:1], v[18:19], v[18:19]
	s_nop 0
	v_add_f32_e32 v0, v83, v0
	v_add_f32_e32 v2, v0, v1
	s_waitcnt lgkmcnt(0)
	v_pk_fma_f32 v[16:17], v[8:9], v[64:65], v[194:195] op_sel_hi:[1,0,1] neg_lo:[0,0,1] neg_hi:[0,0,1]
	s_nop 0
	v_pk_mul_f32 v[0:1], v[16:17], v[16:17]
	s_nop 0
	v_add_f32_e32 v0, v2, v0
	v_add_f32_e32 v2, v0, v1
	s_waitcnt lgkmcnt(0)
	v_pk_fma_f32 v[8:9], v[10:11], v[64:65], v[196:197] op_sel_hi:[1,0,1] neg_lo:[0,0,1] neg_hi:[0,0,1]
	s_nop 0
	v_pk_mul_f32 v[0:1], v[8:9], v[8:9]
	v_mul_u32_u24_e32 v11, 0x110, v158
	v_add_f32_e32 v0, v2, v0
	v_add_f32_e32 v2, v0, v1
	s_waitcnt lgkmcnt(0)
	v_pk_fma_f32 v[4:5], v[12:13], v[64:65], v[198:199] op_sel_hi:[1,0,1] neg_lo:[0,0,1] neg_hi:[0,0,1]
	s_nop 0
	v_pk_mul_f32 v[0:1], v[4:5], v[4:5]
	s_nop 0
	v_add_f32_e32 v0, v2, v0
	v_add_f32_e32 v2, v0, v1
	s_waitcnt lgkmcnt(0)
	v_pk_fma_f32 v[6:7], v[14:15], v[64:65], v[200:201] op_sel_hi:[1,0,1] neg_lo:[0,0,1] neg_hi:[0,0,1]
	s_nop 0
	v_pk_mul_f32 v[0:1], v[6:7], v[6:7]
	s_nop 0
	v_add_f32_e32 v0, v2, v0
	v_add_f32_e32 v0, v0, v1
	ds_bpermute_b32 v1, v145, v0
	s_waitcnt lgkmcnt(0)
; #define LAS __attribute__((address_space(3)))
; __device__ __forceinline__ unsigned cvt_pk_bf16(float lo, float hi) { unsigned r; asm volatile("v_cvt_pk_bf16_f32 %0, %1, %2" : "=v"(r) : "v"(lo), "v"(hi)); return r; }
; __device__ __forceinline__ void attn_unit(LAS unsigned char* lds, const bf16_t* __restrict__ U3, const bf16_t* __restrict__ VT, bf16_t* __restrict__ MIX, ...
;     ...
;         const float rs = rsqrtf(ss * (1.0f / 128.0f) + EPS) * 0.8f;
;         {
;             LAS unsigned char* stg = lds + 65536 + (w & 3) * 8704;
; #pragma unroll
;             for (int d0 = 0; d0 < 4; ++d0)
; #pragma unroll
;                 for (int rg = 0; rg < 4; ++rg) { const int dv = 32 * d0 + 8 * rg; const f32x4 gn = *(const f32x4*)(gain + dv + 4 * hi);
;                     u32x2 wv; wv.x = cvt_pk_bf16(o[d0][4 * rg] * rs * gn.x, o[d0][4 * rg + 1] * rs * gn.y); wv.y = cvt_pk_bf16(o[d0][4 * rg + 2] * rs * gn.z, o[d0][4 * rg + 3] * rs * gn.w);
;                     *(LAS u32x2*)(stg + r32 * 272 + (dv + 4 * hi) * 2) = wv; }
;             asm volatile("s_waitcnt lgkmcnt(0)" ::: "memory");
;             bf16_t* op = MIX + (size_t)(rowbase + qw0 - NMETA + (lane >> 4)) * D + h * 128 + (lane & 15) * 8;
	v_add_f32_e32 v0, v0, v1
	v_fmamk_f32 v0, v0, 0x3c000000, v205
	v_cmp_gt_f32_e32 vcc, s92, v0
	v_mul_f32_e32 v1, 0x4b800000, v0
	s_nop 0
	v_cndmask_b32_e32 v0, v0, v1, vcc
	v_rsq_f32_e32 v0, v0
	s_nop 0
	v_mul_f32_e32 v1, 0x45800000, v0
	v_cndmask_b32_e32 v0, v0, v1, vcc
	v_mul_f32_e32 v10, 0x3f4ccccd, v0
	v_mul_f32_e32 v12, v66, v10
	v_mul_f32_e32 v0, v96, v12
	v_mul_f32_e32 v12, v65, v10
	v_mul_f32_e32 v1, v97, v12
	v_cvt_pk_bf16_f32 v12, v0, v1
	v_mul_f32_e32 v0, v50, v10
	v_mul_f32_e32 v0, v98, v0
	v_mul_f32_e32 v1, v51, v10
	v_mul_f32_e32 v1, v99, v1
	v_cvt_pk_bf16_f32 v13, v0, v1
	v_add3_u32 v0, s10, v11, v157
	ds_write_b64 v0, v[12:13]
	v_mul_f32_e32 v1, v48, v10
	v_mul_f32_e32 v2, v49, v10
	v_mul_f32_e32 v3, v53, v10
	v_mul_f32_e32 v1, v100, v1
	v_mul_f32_e32 v2, v101, v2
	v_cvt_pk_bf16_f32 v2, v1, v2
	v_mul_f32_e32 v1, v52, v10
	v_mul_f32_e32 v3, v103, v3
	v_mul_f32_e32 v1, v102, v1
	v_cvt_pk_bf16_f32 v3, v1, v3
	ds_write_b64 v0, v[2:3] offset:16
	v_mul_f32_e32 v1, v55, v10
	v_mul_f32_e32 v2, v54, v10
	v_mul_f32_e32 v3, v58, v10
	v_mul_f32_e32 v1, v104, v1
	v_mul_f32_e32 v2, v105, v2
	v_cvt_pk_bf16_f32 v2, v1, v2
	v_mul_f32_e32 v1, v67, v10
	v_mul_f32_e32 v3, v107, v3
	v_mul_f32_e32 v1, v106, v1
	v_cvt_pk_bf16_f32 v3, v1, v3
	ds_write_b64 v0, v[2:3] offset:32
	v_mul_f32_e32 v1, v57, v10
	v_mul_f32_e32 v2, v56, v10
	v_mul_f32_e32 v3, v60, v10
	v_mul_f32_e32 v1, v1, v108
	v_mul_f32_e32 v2, v2, v109
	v_cvt_pk_bf16_f32 v2, v1, v2
	v_mul_f32_e32 v1, v61, v10
	v_mul_f32_e32 v3, v3, v111
	v_mul_f32_e32 v1, v1, v110
	v_cvt_pk_bf16_f32 v3, v1, v3
	ds_write_b64 v0, v[2:3] offset:48
	v_mul_f32_e32 v1, v59, v10
	v_mul_f32_e32 v2, v32, v10
	v_mul_f32_e32 v3, v62, v10
	v_mul_f32_e32 v1, v1, v112
	v_mul_f32_e32 v2, v2, v113
	v_cvt_pk_bf16_f32 v2, v1, v2
	v_mul_f32_e32 v1, v63, v10
	v_mul_f32_e32 v3, v3, v115
	v_mul_f32_e32 v1, v1, v114
	v_cvt_pk_bf16_f32 v3, v1, v3
	ds_write_b64 v0, v[2:3] offset:64
	v_mul_f32_e32 v1, v34, v10
	v_mul_f32_e32 v2, v33, v10
	v_mul_f32_e32 v3, v38, v10
	v_mul_f32_e32 v1, v1, v116
	v_mul_f32_e32 v2, v2, v117
	v_cvt_pk_bf16_f32 v2, v1, v2
	v_mul_f32_e32 v1, v68, v10
	v_mul_f32_e32 v3, v3, v119
	v_mul_f32_e32 v1, v1, v118
	v_cvt_pk_bf16_f32 v3, v1, v3
	ds_write_b64 v0, v[2:3] offset:80
	v_mul_f32_e32 v1, v36, v10
	v_mul_f32_e32 v2, v35, v10
	v_mul_f32_e32 v3, v42, v10
	v_mul_f32_e32 v1, v1, v120
	v_mul_f32_e32 v2, v2, v121
	v_cvt_pk_bf16_f32 v2, v1, v2
	v_mul_f32_e32 v1, v69, v10
	v_mul_f32_e32 v3, v3, v123
	v_mul_f32_e32 v1, v1, v122
	v_cvt_pk_bf16_f32 v3, v1, v3
	ds_write_b64 v0, v[2:3] offset:96
	v_mul_f32_e32 v1, v39, v10
	v_mul_f32_e32 v2, v37, v10
	v_mul_f32_e32 v3, v46, v10
	v_mul_f32_e32 v1, v1, v124
	v_mul_f32_e32 v2, v2, v125
	v_cvt_pk_bf16_f32 v2, v1, v2
	v_mul_f32_e32 v1, v71, v10
	v_mul_f32_e32 v3, v3, v127
	v_mul_f32_e32 v1, v1, v126
	v_cvt_pk_bf16_f32 v3, v1, v3
	ds_write_b64 v0, v[2:3] offset:112
	v_mul_f32_e32 v1, v43, v10
	v_mul_f32_e32 v2, v41, v10
	v_mul_f32_e32 v3, v74, v10
	v_mul_f32_e32 v1, v1, v218
	v_mul_f32_e32 v2, v2, v219
	v_cvt_pk_bf16_f32 v2, v1, v2
	v_mul_f32_e32 v1, v75, v10
	v_mul_f32_e32 v3, v3, v221
	v_mul_f32_e32 v1, v1, v220
	v_cvt_pk_bf16_f32 v3, v1, v3
	ds_write_b64 v0, v[2:3] offset:128
	v_mul_f32_e32 v1, v47, v10
	v_mul_f32_e32 v2, v44, v10
	v_mul_f32_e32 v3, v76, v10
	v_mul_f32_e32 v1, v1, v222
	v_mul_f32_e32 v2, v2, v223
	v_cvt_pk_bf16_f32 v2, v1, v2
	v_mul_f32_e32 v1, v77, v10
	v_mul_f32_e32 v3, v3, v225
	v_mul_f32_e32 v1, v1, v224
	v_cvt_pk_bf16_f32 v3, v1, v3
	ds_write_b64 v0, v[2:3] offset:144
	v_mul_f32_e32 v1, v73, v10
	v_mul_f32_e32 v2, v72, v10
	v_mul_f32_e32 v3, v45, v10
	v_mul_f32_e32 v1, v1, v226
	v_mul_f32_e32 v2, v2, v227
	v_cvt_pk_bf16_f32 v2, v1, v2
	v_mul_f32_e32 v1, v70, v10
	v_mul_f32_e32 v3, v3, v229
	v_mul_f32_e32 v1, v1, v228
	v_cvt_pk_bf16_f32 v3, v1, v3
	ds_write_b64 v0, v[2:3] offset:160
	v_mul_f32_e32 v1, v40, v10
	v_mul_f32_e32 v2, v28, v10
	v_mul_f32_e32 v3, v26, v10
	v_mul_f32_e32 v1, v1, v230
	v_mul_f32_e32 v2, v2, v231
	v_cvt_pk_bf16_f32 v2, v1, v2
	v_mul_f32_e32 v1, v27, v10
	v_mul_f32_e32 v3, v3, v233
	v_mul_f32_e32 v1, v1, v232
	v_cvt_pk_bf16_f32 v3, v1, v3
	ds_write_b64 v0, v[2:3] offset:176
	v_mul_f32_e32 v1, v25, v10
	v_mul_f32_e32 v2, v24, v10
	v_mul_f32_e32 v3, v22, v10
	v_mul_f32_e32 v1, v1, v234
	v_mul_f32_e32 v2, v2, v235
	v_cvt_pk_bf16_f32 v2, v1, v2
	v_mul_f32_e32 v1, v23, v10
	v_mul_f32_e32 v3, v3, v237
	v_mul_f32_e32 v1, v1, v236
	v_cvt_pk_bf16_f32 v3, v1, v3
	ds_write_b64 v0, v[2:3] offset:192
	v_mul_f32_e32 v1, v21, v10
	v_mul_f32_e32 v2, v20, v10
	v_mul_f32_e32 v3, v19, v10
	v_mul_f32_e32 v1, v1, v238
	v_mul_f32_e32 v2, v2, v239
	v_cvt_pk_bf16_f32 v2, v1, v2
	v_mul_f32_e32 v1, v18, v10
	v_mul_f32_e32 v3, v3, v241
	v_mul_f32_e32 v1, v1, v240
	v_cvt_pk_bf16_f32 v3, v1, v3
	ds_write_b64 v0, v[2:3] offset:208
	v_mul_f32_e32 v1, v16, v10
	v_mul_f32_e32 v2, v17, v10
	v_mul_f32_e32 v3, v9, v10
	v_mul_f32_e32 v1, v1, v242
	v_mul_f32_e32 v2, v2, v243
	v_cvt_pk_bf16_f32 v2, v1, v2
	v_mul_f32_e32 v1, v8, v10
	v_mul_f32_e32 v3, v3, v245
	v_mul_f32_e32 v1, v1, v244
	v_cvt_pk_bf16_f32 v3, v1, v3
	ds_write_b64 v0, v[2:3] offset:224
	v_mul_f32_e32 v1, v4, v10
	v_mul_f32_e32 v2, v5, v10
	v_mul_f32_e32 v3, v7, v10
	v_mul_f32_e32 v1, v1, v246
	v_mul_f32_e32 v2, v2, v247
	v_cvt_pk_bf16_f32 v2, v1, v2
	v_mul_f32_e32 v1, v6, v10
	v_mul_f32_e32 v3, v3, v249
	v_mul_f32_e32 v1, v1, v248
	v_cvt_pk_bf16_f32 v3, v1, v3
	ds_write_b64 v0, v[2:3] offset:240
	v_or_b32_e32 v0, s63, v156
	v_add_u32_e32 v0, s62, v0
	v_ashrrev_i32_e32 v1, 31, v0
	v_lshlrev_b64 v[0:1], 11, v[0:1]
	v_lshlrev_b32_e32 v2, 4, v155
	v_lshl_add_u64 v[0:1], s[22:23], 0, v[0:1]
	v_and_b32_e32 v160, 0xf0, v2
	v_lshl_add_u64 v[4:5], v[0:1], 0, v[160:161]
	v_mul_u32_u24_e32 v0, 0x110, v156
	s_waitcnt lgkmcnt(0)
; #define LAS __attribute__((address_space(3)))
; __device__ __forceinline__ void attn_unit(LAS unsigned char* lds, const bf16_t* __restrict__ U3, const bf16_t* __restrict__ VT, bf16_t* __restrict__ MIX, ...
;     ...
;             bf16_t* op = MIX + (size_t)(rowbase + qw0 - NMETA + (lane >> 4)) * D + h * 128 + (lane & 15) * 8;
; #pragma unroll
;             for (int i = 0; i < 8; ++i) { const u32x4 v = *(const LAS u32x4*)(stg + (i * 4 + (lane >> 4)) * 272 + (lane & 15) * 16); *(u32x4*)(op + (size_t)(i * 4) * D) = v; }
	v_add3_u32 v8, s10, v160, v0
	ds_read_b128 v[0:3], v8
	s_movk_i32 s10, 0x2000
	v_add_co_u32_e32 v6, vcc, s10, v4
	s_movk_i32 s10, 0x4000
	s_waitcnt lgkmcnt(0)
	global_store_dwordx4 v[4:5], v[0:3], off
	ds_read_b128 v[0:3], v8 offset:1088
	v_addc_co_u32_e32 v7, vcc, 0, v5, vcc
	s_waitcnt lgkmcnt(0)
	global_store_dwordx4 v[6:7], v[0:3], off
	ds_read_b128 v[0:3], v8 offset:2176
	v_add_co_u32_e32 v6, vcc, s10, v4
	s_movk_i32 s10, 0x6000
	s_nop 0
	v_addc_co_u32_e32 v7, vcc, 0, v5, vcc
	s_waitcnt lgkmcnt(0)
	global_store_dwordx4 v[6:7], v[0:3], off
	ds_read_b128 v[0:3], v8 offset:3264
	v_add_co_u32_e32 v6, vcc, s10, v4
	s_mov_b32 s10, 0x8000
	s_nop 0
	v_addc_co_u32_e32 v7, vcc, 0, v5, vcc
	s_waitcnt lgkmcnt(0)
	global_store_dwordx4 v[6:7], v[0:3], off
	ds_read_b128 v[0:3], v8 offset:4352
	v_add_co_u32_e32 v6, vcc, s10, v4
	s_nop 1
	v_addc_co_u32_e32 v7, vcc, 0, v5, vcc
	s_waitcnt lgkmcnt(0)
	global_store_dwordx4 v[6:7], v[0:3], off
	ds_read_b128 v[0:3], v8 offset:5440
	v_add_co_u32_e32 v6, vcc, 0xa000, v4
	s_nop 1
	v_addc_co_u32_e32 v7, vcc, 0, v5, vcc
	s_waitcnt lgkmcnt(0)
	global_store_dwordx4 v[6:7], v[0:3], off
	ds_read_b128 v[0:3], v8 offset:6528
	v_add_co_u32_e32 v6, vcc, 0xc000, v4
	s_nop 1
	v_addc_co_u32_e32 v7, vcc, 0, v5, vcc
	s_waitcnt lgkmcnt(0)
	global_store_dwordx4 v[6:7], v[0:3], off
	ds_read_b128 v[0:3], v8 offset:7616
	v_add_co_u32_e32 v4, vcc, 0xe000, v4
	s_nop 1
	v_addc_co_u32_e32 v5, vcc, 0, v5, vcc
	s_waitcnt lgkmcnt(0)
	global_store_dwordx4 v[4:5], v[0:3], off
	s_branch .LBB0_498
